# P7 combine: the four diff-attention loads of a row issued together with the NSA-branch loads (own address and destination registers) so the row's two cold round trips overlap
# speedup vs baseline: 1.0008x; 1.0008x over previous
; __device__ __forceinline__ u32x4 pack8v(f32x4 a, f32x4 b) { u32x4 w; w.x = cvtpk(a[0], a[1]); w.y = cvtpk(a[2], a[3]); w.z = cvtpk(b[0], b[1]); w.w = cvtpk(b[2], b[3]); return w; }
; #define lane lane_id()
; __global__ void __launch_bounds__(512, 2) mega_fwd(Args args) {
;     ...
;             const int b = m >> 14, s = m & (SEQ - 1);
;             {
;                 const int h = lane >> 3, d = (lane & 7) * 16; const size_t off = ((size_t)(b * 8 + h) * SEQ + s) * 128 + d;
;                 const float g0 = GN[(size_t)m * 24 + h * 3], g1 = GN[(size_t)m * 24 + h * 3 + 1], g2 = GN[(size_t)m * 24 + h * 3 + 2];
; #pragma unroll
;                 for (int e = 0; e < 2; ++e) { f32x4 c0, c1, s0, s1, w0, w1;
;                     pg8::unpack8(*(const u32x4*)(OC + off + e * 8), c0, c1); pg8::unpack8(*(const u32x4*)(OS + off + e * 8), s0, s1); pg8::unpack8(*(const u32x4*)(OW + off + e * 8), w0, w1);
;                     *(u32x4*)(ONSA + (size_t)m * 1024 + h * 128 + d + e * 8) = pg8::pack8v(c0 * g0 + s0 * g1 + w0 * g2, c1 * g0 + s1 * g1 + w1 * g2); }
;             }
;             {
;                 const int h = lane >> 4, j = (lane & 15) * 16, vhalf = j >> 7, d = j & 127;
;                 const size_t o1 = ((size_t)(((b * 4 + h) * 2 + 0) * 2 + vhalf) * SEQ + s) * 128 + d, o2 = ((size_t)(((b * 4 + h) * 2 + 1) * 2 + vhalf) * SEQ + s) * 128 + d;
;                 f32x4 v[4]; float ss = 0.f;
; #pragma unroll
;                 for (int e = 0; e < 2; ++e) { f32x4 a0, a1, b0, b1; pg8::unpack8(*(const u32x4*)(O12 + o1 + e * 8), a0, a1); pg8::unpack8(*(const u32x4*)(O12 + o2 + e * 8), b0, b1);
.LBB0_1640:
	s_and_b32 s6, s28, 0x3fff
	v_mbcnt_lo_u32_b32 v0, -1, 0
	v_mbcnt_hi_u32_b32 v0, -1, v0
	s_ashr_i32 s25, s28, 11
	v_mbcnt_lo_u32_b32 v7, -1, 0
	v_mbcnt_hi_u32_b32 v7, -1, v7
	v_lshrrev_b32_e32 v8, 3, v0
	v_bfe_u32 v12, v0, 3, 3
	v_lshlrev_b32_e32 v0, 4, v7
	s_and_b32 s24, s25, -8
	s_lshl_b32 s29, s6, 7
	v_and_b32_e32 v13, 0x70, v0
	v_mul_u32_u24_e32 v0, 3, v12
	s_add_u32 s36, s18, s1
	v_bfi_b32 v8, 7, v8, s25
	v_lshlrev_b32_e32 v0, 2, v0
	s_addc_u32 s37, s19, s0
	v_and_b32_e32 v7, 7, v7
	v_ashrrev_i32_e32 v9, 31, v8
	v_lshl_add_u64 v[10:11], s[36:37], 0, v[0:1]
	v_lshlrev_b32_e32 v7, 5, v7
	v_lshlrev_b64 v[8:9], 21, v[8:9]
	s_add_u32 s42, s18, s8
	v_add_co_u32_e32 v10, vcc, s15, v10
	v_lshl_or_b32 v0, v12, 8, v7
	v_or3_b32 v8, v8, s29, v13
	v_addc_co_u32_e32 v11, vcc, 0, v11, vcc
	s_addc_u32 s43, s19, s9
	global_load_dwordx3 v[20:22], v[10:11], off offset:2048
	v_lshlrev_b64 v[8:9], 1, v[8:9]
	v_lshl_add_u64 v[10:11], s[42:43], 0, v[0:1]
	v_lshl_add_u64 v[24:25], s[16:17], 0, v[8:9]
	v_add_co_u32_e32 v30, vcc, s21, v10
	v_lshl_add_u64 v[26:27], s[50:51], 0, v[8:9]
	v_lshl_add_u64 v[28:29], s[44:45], 0, v[8:9]
	v_addc_co_u32_e32 v31, vcc, 0, v11, vcc
	global_load_dwordx4 v[8:11], v[24:25], off
	global_load_dwordx4 v[12:15], v[26:27], off
	global_load_dwordx4 v[16:19], v[28:29], off
	s_lshl_b32 s29, s24, 1
	s_lshl_b32 s6, s6, 8
	s_add_i32 s28, s28, s14
	s_add_u32 s1, s1, s20
	s_addc_u32 s0, s0, s12
	s_add_u32 s8, s8, s10
	s_addc_u32 s9, s9, s11
	s_cmp_lt_i32 s28, 0x8000
	v_mbcnt_lo_u32_b32 v76, -1, 0
	v_mbcnt_hi_u32_b32 v76, -1, v76
	v_bfe_u32 v77, v76, 4, 2
	v_lshlrev_b32_e32 v78, 4, v76
	v_lshlrev_b32_e32 v79, 5, v76
	v_bfe_u32 v80, v78, 7, 1
	v_lshlrev_b32_e32 v81, 2, v77
	v_and_b32_e32 v82, 0xe0, v79
	v_mov_b32_e32 v83, 0
	v_or3_b32 v84, v81, s29, v80
	v_or_b32_e32 v86, 2, v84
	v_ashrrev_i32_e32 v85, 31, v84
	v_ashrrev_i32_e32 v87, 31, v86
	v_lshlrev_b64 v[84:85], 22, v[84:85]
	v_lshlrev_b64 v[86:87], 22, v[86:87]
	v_lshl_add_u64 v[84:85], s[30:31], 0, v[84:85]
	v_lshl_add_u64 v[86:87], s[30:31], 0, v[86:87]
	v_lshl_add_u64 v[84:85], v[84:85], 0, s[6:7]
	v_lshl_add_u64 v[86:87], v[86:87], 0, s[6:7]
	v_lshl_add_u64 v[84:85], v[84:85], 0, v[82:83]
	v_lshl_add_u64 v[86:87], v[86:87], 0, v[82:83]
	global_load_dwordx4 v[60:63], v[84:85], off
	global_load_dwordx4 v[64:67], v[84:85], off offset:16
	global_load_dwordx4 v[68:71], v[86:87], off
	global_load_dwordx4 v[72:75], v[86:87], off offset:16
	s_waitcnt vmcnt(7)
	v_mov_b32_e32 v0, v22
	s_waitcnt vmcnt(6)
	v_lshlrev_b32_e32 v22, 16, v8
	s_waitcnt vmcnt(5)
	v_lshlrev_b32_e32 v34, 16, v12
	v_and_b32_e32 v35, 0xffff0000, v12
	v_lshlrev_b32_e32 v12, 16, v13
	v_and_b32_e32 v13, 0xffff0000, v13
	v_lshlrev_b32_e32 v36, 16, v14
	v_and_b32_e32 v37, 0xffff0000, v14
	v_lshlrev_b32_e32 v14, 16, v15
	v_and_b32_e32 v15, 0xffff0000, v15
	v_and_b32_e32 v23, 0xffff0000, v8
	v_lshlrev_b32_e32 v8, 16, v9
	v_and_b32_e32 v9, 0xffff0000, v9
	v_lshlrev_b32_e32 v32, 16, v10
	v_and_b32_e32 v33, 0xffff0000, v10
	v_lshlrev_b32_e32 v10, 16, v11
	v_and_b32_e32 v11, 0xffff0000, v11
	v_pk_mul_f32 v[12:13], v[20:21], v[12:13] op_sel:[1,0]
	v_pk_mul_f32 v[34:35], v[20:21], v[34:35] op_sel:[1,0]
	v_pk_mul_f32 v[14:15], v[20:21], v[14:15] op_sel:[1,0]
	v_pk_mul_f32 v[36:37], v[20:21], v[36:37] op_sel:[1,0]
	s_waitcnt vmcnt(4)
	v_lshlrev_b32_e32 v38, 16, v16
	v_and_b32_e32 v39, 0xffff0000, v16
	v_lshlrev_b32_e32 v16, 16, v17
	v_and_b32_e32 v17, 0xffff0000, v17
	v_lshlrev_b32_e32 v40, 16, v18
	v_and_b32_e32 v41, 0xffff0000, v18
	v_lshlrev_b32_e32 v18, 16, v19
	v_and_b32_e32 v19, 0xffff0000, v19
	v_pk_fma_f32 v[22:23], v[20:21], v[22:23], v[34:35] op_sel_hi:[0,1,1]
	v_pk_fma_f32 v[8:9], v[20:21], v[8:9], v[12:13] op_sel_hi:[0,1,1]
	v_pk_fma_f32 v[12:13], v[20:21], v[32:33], v[36:37] op_sel_hi:[0,1,1]
	v_pk_fma_f32 v[10:11], v[20:21], v[10:11], v[14:15] op_sel_hi:[0,1,1]
	v_pk_fma_f32 v[14:15], v[0:1], v[16:17], v[8:9] op_sel_hi:[0,1,1]
	v_pk_fma_f32 v[8:9], v[0:1], v[38:39], v[22:23] op_sel_hi:[0,1,1]
	v_pk_fma_f32 v[16:17], v[0:1], v[18:19], v[10:11] op_sel_hi:[0,1,1]
	v_pk_fma_f32 v[10:11], v[0:1], v[40:41], v[12:13] op_sel_hi:[0,1,1]
	v_cvt_pk_bf16_f32 v8, v8, v9
	v_cvt_pk_bf16_f32 v9, v14, v15
	v_cvt_pk_bf16_f32 v10, v10, v11
	v_cvt_pk_bf16_f32 v11, v16, v17
	global_store_dwordx4 v[30:31], v[8:11], off offset:2048
	global_load_dwordx4 v[8:11], v[24:25], off offset:16
	s_nop 0
	global_load_dwordx4 v[12:15], v[26:27], off offset:16
	global_load_dwordx4 v[16:19], v[28:29], off offset:16
	s_waitcnt vmcnt(2)
	v_lshlrev_b32_e32 v22, 16, v8
	s_waitcnt vmcnt(1)
	v_lshlrev_b32_e32 v26, 16, v12
	v_and_b32_e32 v27, 0xffff0000, v12
	v_lshlrev_b32_e32 v12, 16, v13
	v_and_b32_e32 v13, 0xffff0000, v13
	v_lshlrev_b32_e32 v28, 16, v14
	v_and_b32_e32 v29, 0xffff0000, v14
	v_lshlrev_b32_e32 v14, 16, v15
	v_and_b32_e32 v15, 0xffff0000, v15
	v_and_b32_e32 v23, 0xffff0000, v8
	v_lshlrev_b32_e32 v8, 16, v9
	v_and_b32_e32 v9, 0xffff0000, v9
	v_lshlrev_b32_e32 v24, 16, v10
	v_and_b32_e32 v25, 0xffff0000, v10
	v_lshlrev_b32_e32 v10, 16, v11
	v_and_b32_e32 v11, 0xffff0000, v11
	v_pk_mul_f32 v[12:13], v[20:21], v[12:13] op_sel:[1,0]
	v_pk_mul_f32 v[26:27], v[20:21], v[26:27] op_sel:[1,0]
	v_pk_mul_f32 v[14:15], v[20:21], v[14:15] op_sel:[1,0]
	v_pk_mul_f32 v[28:29], v[20:21], v[28:29] op_sel:[1,0]
	s_waitcnt vmcnt(0)
; __device__ __forceinline__ u32x4 pack8v(f32x4 a, f32x4 b) { u32x4 w; w.x = cvtpk(a[0], a[1]); w.y = cvtpk(a[2], a[3]); w.z = cvtpk(b[0], b[1]); w.w = cvtpk(b[2], b[3]); return w; }
; #define lane lane_id()
; __global__ void __launch_bounds__(512, 2) mega_fwd(Args args) {
;     ...
;                     pg8::unpack8(*(const u32x4*)(OC + off + e * 8), c0, c1); pg8::unpack8(*(const u32x4*)(OS + off + e * 8), s0, s1); pg8::unpack8(*(const u32x4*)(OW + off + e * 8), w0, w1);
;                     *(u32x4*)(ONSA + (size_t)m * 1024 + h * 128 + d + e * 8) = pg8::pack8v(c0 * g0 + s0 * g1 + w0 * g2, c1 * g0 + s1 * g1 + w1 * g2); }
;             }
;             {
;                 const int h = lane >> 4, j = (lane & 15) * 16, vhalf = j >> 7, d = j & 127;
;                 const size_t o1 = ((size_t)(((b * 4 + h) * 2 + 0) * 2 + vhalf) * SEQ + s) * 128 + d, o2 = ((size_t)(((b * 4 + h) * 2 + 1) * 2 + vhalf) * SEQ + s) * 128 + d;
;                 f32x4 v[4]; float ss = 0.f;
; #pragma unroll
;                 for (int e = 0; e < 2; ++e) { f32x4 a0, a1, b0, b1; pg8::unpack8(*(const u32x4*)(O12 + o1 + e * 8), a0, a1); pg8::unpack8(*(const u32x4*)(O12 + o2 + e * 8), b0, b1);
;     ...
;                 const f32x4* gp = (const f32x4*)(hg + h * 256 + j);
	v_lshlrev_b32_e32 v32, 16, v16
	v_and_b32_e32 v33, 0xffff0000, v16
	v_lshlrev_b32_e32 v16, 16, v17
	v_and_b32_e32 v17, 0xffff0000, v17
	v_lshlrev_b32_e32 v34, 16, v18
	v_and_b32_e32 v35, 0xffff0000, v18
	v_lshlrev_b32_e32 v18, 16, v19
	v_and_b32_e32 v19, 0xffff0000, v19
	v_pk_fma_f32 v[22:23], v[20:21], v[22:23], v[26:27] op_sel_hi:[0,1,1]
	v_pk_fma_f32 v[8:9], v[20:21], v[8:9], v[12:13] op_sel_hi:[0,1,1]
	v_pk_fma_f32 v[12:13], v[20:21], v[24:25], v[28:29] op_sel_hi:[0,1,1]
	v_pk_fma_f32 v[10:11], v[20:21], v[10:11], v[14:15] op_sel_hi:[0,1,1]
	v_pk_fma_f32 v[14:15], v[0:1], v[16:17], v[8:9] op_sel_hi:[0,1,1]
	v_pk_fma_f32 v[8:9], v[0:1], v[32:33], v[22:23] op_sel_hi:[0,1,1]
	v_pk_fma_f32 v[16:17], v[0:1], v[18:19], v[10:11] op_sel_hi:[0,1,1]
	v_pk_fma_f32 v[10:11], v[0:1], v[34:35], v[12:13] op_sel_hi:[0,1,1]
	v_cvt_pk_bf16_f32 v8, v8, v9
	v_cvt_pk_bf16_f32 v9, v14, v15
	v_cvt_pk_bf16_f32 v10, v10, v11
	v_cvt_pk_bf16_f32 v11, v16, v17
	global_store_dwordx4 v[30:31], v[8:11], off offset:2064
	v_mbcnt_lo_u32_b32 v0, -1, 0
	v_mbcnt_hi_u32_b32 v0, -1, v0
	v_mbcnt_lo_u32_b32 v7, -1, 0
	v_mbcnt_hi_u32_b32 v7, -1, v7
	s_nop 0
	v_bfe_u32 v26, v0, 4, 2
	v_lshlrev_b32_e32 v0, 4, v7
	v_lshlrev_b32_e32 v8, 5, v7
	v_bfe_u32 v9, v0, 7, 1
	v_lshlrev_b32_e32 v10, 2, v26
	v_and_b32_e32 v27, 0xf0, v0
	v_and_b32_e32 v0, 0xe0, v8
	v_or3_b32 v8, v10, s29, v9
	v_or_b32_e32 v10, 2, v8
	v_ashrrev_i32_e32 v9, 31, v8
	v_ashrrev_i32_e32 v11, 31, v10
	v_lshlrev_b64 v[8:9], 22, v[8:9]
	v_lshlrev_b64 v[10:11], 22, v[10:11]
	v_lshl_add_u64 v[8:9], s[30:31], 0, v[8:9]
	v_lshl_add_u64 v[10:11], s[30:31], 0, v[10:11]
	v_lshl_add_u64 v[8:9], v[8:9], 0, s[6:7]
	v_lshl_add_u64 v[16:17], v[10:11], 0, s[6:7]
	v_lshl_add_u64 v[12:13], v[8:9], 0, v[0:1]
	v_lshl_add_u64 v[20:21], v[16:17], 0, v[0:1]
	v_lshlrev_b32_e32 v0, 10, v26
	v_and_b32_e32 v7, 15, v7
	s_waitcnt lgkmcnt(0)
	v_lshl_add_u64 v[24:25], s[4:5], 0, v[0:1]
	v_lshlrev_b32_e32 v0, 2, v27
	v_lshlrev_b32_e32 v7, 5, v7
	v_lshl_add_u64 v[32:33], v[24:25], 0, v[0:1]
	v_lshl_or_b32 v0, v26, 9, v7
	global_load_dwordx4 v[24:27], v[32:33], off offset:16
	global_load_dwordx4 v[28:31], v[32:33], off
	v_lshl_add_u64 v[34:35], s[42:43], 0, v[0:1]
	v_add_co_u32_e32 v34, vcc, s27, v34
	s_waitcnt vmcnt(5)
	v_lshlrev_b32_e32 v36, 16, v60
	v_and_b32_e32 v37, 0xffff0000, v60
	v_lshlrev_b32_e32 v8, 16, v61
	v_and_b32_e32 v9, 0xffff0000, v61
	v_lshlrev_b32_e32 v38, 16, v62
	v_and_b32_e32 v39, 0xffff0000, v62
	v_lshlrev_b32_e32 v10, 16, v63
	v_and_b32_e32 v11, 0xffff0000, v63
	s_waitcnt vmcnt(3)
	v_lshlrev_b32_e32 v44, 16, v68
	v_and_b32_e32 v45, 0xffff0000, v68
	v_lshlrev_b32_e32 v16, 16, v69
	v_and_b32_e32 v17, 0xffff0000, v69
	v_lshlrev_b32_e32 v46, 16, v70
	v_and_b32_e32 v47, 0xffff0000, v70
	v_lshlrev_b32_e32 v18, 16, v71
	v_and_b32_e32 v19, 0xffff0000, v71
	v_lshlrev_b32_e32 v40, 16, v64
	v_and_b32_e32 v41, 0xffff0000, v64
	v_lshlrev_b32_e32 v12, 16, v65
	v_and_b32_e32 v13, 0xffff0000, v65
	v_lshlrev_b32_e32 v42, 16, v66
	v_and_b32_e32 v43, 0xffff0000, v66
	v_lshlrev_b32_e32 v14, 16, v67
	v_and_b32_e32 v15, 0xffff0000, v67
	s_waitcnt vmcnt(2)
; __device__ __forceinline__ u32x4 pack8v(f32x4 a, f32x4 b) { u32x4 w; w.x = cvtpk(a[0], a[1]); w.y = cvtpk(a[2], a[3]); w.z = cvtpk(b[0], b[1]); w.w = cvtpk(b[2], b[3]); return w; }
; __global__ void __launch_bounds__(512, 2) mega_fwd(Args args) {
;     ...
;                 for (int e = 0; e < 2; ++e) { f32x4 a0, a1, b0, b1; pg8::unpack8(*(const u32x4*)(O12 + o1 + e * 8), a0, a1); pg8::unpack8(*(const u32x4*)(O12 + o2 + e * 8), b0, b1);
;                     v[2 * e] = a0 - b0 * lam; v[2 * e + 1] = a1 - b1 * lam; }
; #pragma unroll
;                 for (int e = 0; e < 4; ++e) ss += (v[e].x * v[e].x + v[e].y * v[e].y) + (v[e].z * v[e].z + v[e].w * v[e].w);
;                 ss = row16_sum(ss);
;                 const float rstd = rsqrtf(ss * (1.f / 256.f) + RMS_EPS) * 0.8f;
;                 const f32x4* gp = (const f32x4*)(hg + h * 256 + j);
; #pragma unroll
;                 for (int e = 0; e < 2; ++e) *(u32x4*)(OD + (size_t)m * 1024 + h * 256 + j + e * 8) = pg8::pack8v(v[2 * e] * rstd * gp[2 * e], v[2 * e + 1] * rstd * gp[2 * e + 1]);
	v_lshlrev_b32_e32 v48, 16, v72
	v_and_b32_e32 v49, 0xffff0000, v72
	v_lshlrev_b32_e32 v20, 16, v73
	v_and_b32_e32 v21, 0xffff0000, v73
	v_lshlrev_b32_e32 v50, 16, v74
	v_and_b32_e32 v51, 0xffff0000, v74
	v_lshlrev_b32_e32 v22, 16, v75
	v_and_b32_e32 v23, 0xffff0000, v75
	v_pk_fma_f32 v[36:37], v[2:3], v[44:45], v[36:37] neg_lo:[1,0,0] neg_hi:[1,0,0]
	v_pk_fma_f32 v[8:9], v[4:5], v[16:17], v[8:9]
	v_pk_fma_f32 v[16:17], v[2:3], v[46:47], v[38:39] neg_lo:[1,0,0] neg_hi:[1,0,0]
	v_pk_fma_f32 v[10:11], v[4:5], v[18:19], v[10:11]
	v_pk_fma_f32 v[18:19], v[4:5], v[20:21], v[12:13]
	v_pk_fma_f32 v[20:21], v[2:3], v[48:49], v[40:41] neg_lo:[1,0,0] neg_hi:[1,0,0]
	v_pk_fma_f32 v[22:23], v[4:5], v[22:23], v[14:15]
	v_pk_fma_f32 v[38:39], v[2:3], v[50:51], v[42:43] neg_lo:[1,0,0] neg_hi:[1,0,0]
	v_pk_mul_f32 v[12:13], v[8:9], v[8:9]
	v_pk_mul_f32 v[14:15], v[36:37], v[36:37]
	v_pk_mul_f32 v[40:41], v[10:11], v[10:11]
	v_pk_mul_f32 v[42:43], v[16:17], v[16:17]
	v_pk_mov_b32 v[46:47], v[14:15], v[12:13] op_sel:[1,0]
	v_mov_b32_e32 v15, v13
	v_pk_mov_b32 v[12:13], v[42:43], v[40:41] op_sel:[1,0]
	v_mov_b32_e32 v43, v41
	v_mul_f32_e32 v0, v21, v21
	v_mul_f32_e32 v44, v19, v19
	v_pk_add_f32 v[14:15], v[46:47], v[14:15]
	v_pk_add_f32 v[12:13], v[12:13], v[42:43]
	v_mul_f32_e32 v7, v38, v38
	v_mul_f32_e32 v48, v39, v39
	v_mul_f32_e32 v49, v22, v22
	v_mul_f32_e32 v50, v23, v23
	v_pk_fma_f32 v[40:41], v[20:21], v[20:21], v[0:1] op_sel_hi:[1,1,0]
	v_pk_fma_f32 v[44:45], v[18:19], v[18:19], v[44:45] op_sel_hi:[1,1,0]
	v_pk_add_f32 v[14:15], v[14:15], v[14:15] op_sel:[0,1] op_sel_hi:[1,0]
	v_pk_add_f32 v[12:13], v[12:13], v[12:13] op_sel:[0,1] op_sel_hi:[1,0]
	v_mov_b32_e32 v41, v49
	v_mov_b32_e32 v45, v50
	v_mov_b32_e32 v15, v7
	v_mov_b32_e32 v13, v48
	v_pk_add_f32 v[40:41], v[40:41], v[44:45]
	v_pk_add_f32 v[12:13], v[14:15], v[12:13]
	v_addc_co_u32_e32 v35, vcc, 0, v35, vcc
	v_pk_add_f32 v[12:13], v[12:13], v[40:41]
	s_nop 0
	v_add_f32_e32 v0, v12, v13
	s_nop 1
	v_add_f32_dpp v0, v0, v0 quad_perm:[1,0,3,2] row_mask:0xf bank_mask:0xf bound_ctrl:1
	s_nop 1
	v_add_f32_dpp v0, v0, v0 quad_perm:[2,3,0,1] row_mask:0xf bank_mask:0xf bound_ctrl:1
	s_nop 1
	v_add_f32_dpp v0, v0, v0 row_half_mirror row_mask:0xf bank_mask:0xf bound_ctrl:1
	s_nop 1
	v_add_f32_dpp v0, v0, v0 row_mirror row_mask:0xf bank_mask:0xf bound_ctrl:1
	v_fmamk_f32 v0, v0, 0x3b800000, v6
	v_mul_f32_e32 v7, 0x4b800000, v0
	v_cmp_gt_f32_e32 vcc, s26, v0
	s_nop 1
	v_cndmask_b32_e32 v0, v0, v7, vcc
	v_rsq_f32_e32 v0, v0
	s_nop 0
	v_mul_f32_e32 v7, 0x45800000, v0
	v_cndmask_b32_e32 v0, v0, v7, vcc
	v_mul_f32_e32 v0, 0x3f4ccccd, v0
	v_pk_mul_f32 v[12:13], v[0:1], v[36:37] op_sel_hi:[0,1]
	v_pk_mul_f32 v[8:9], v[0:1], v[8:9] op_sel_hi:[0,1]
	v_pk_mul_f32 v[14:15], v[0:1], v[16:17] op_sel_hi:[0,1]
	v_pk_mul_f32 v[10:11], v[0:1], v[10:11] op_sel_hi:[0,1]
	s_waitcnt vmcnt(0)
	v_pk_mul_f32 v[16:17], v[8:9], v[30:31]
	v_pk_mul_f32 v[8:9], v[12:13], v[28:29]
	v_pk_mul_f32 v[12:13], v[10:11], v[26:27]
	v_pk_mul_f32 v[10:11], v[14:15], v[24:25]
	v_cvt_pk_bf16_f32 v8, v8, v9
	v_cvt_pk_bf16_f32 v9, v16, v17
	v_pk_mul_f32 v[16:17], v[0:1], v[20:21] op_sel_hi:[0,1]
	v_cvt_pk_bf16_f32 v10, v10, v11
	v_cvt_pk_bf16_f32 v11, v12, v13
	global_store_dwordx4 v[34:35], v[8:11], off offset:2048
	global_load_dwordx4 v[8:11], v[32:33], off offset:32
	s_nop 0
	global_load_dwordx4 v[12:15], v[32:33], off offset:48
	v_pk_mul_f32 v[18:19], v[0:1], v[18:19] op_sel_hi:[0,1]
	v_pk_mul_f32 v[20:21], v[0:1], v[38:39] op_sel_hi:[0,1]
	v_pk_mul_f32 v[22:23], v[0:1], v[22:23] op_sel_hi:[0,1]
	s_waitcnt vmcnt(1)
	v_pk_mul_f32 v[10:11], v[18:19], v[10:11]
	v_pk_mul_f32 v[8:9], v[16:17], v[8:9]
	s_waitcnt vmcnt(0)
	v_pk_mul_f32 v[14:15], v[22:23], v[14:15]
	v_pk_mul_f32 v[12:13], v[20:21], v[12:13]
	v_cvt_pk_bf16_f32 v8, v8, v9
	v_cvt_pk_bf16_f32 v9, v10, v11
	s_nop 0
	v_cvt_pk_bf16_f32 v10, v12, v13
	v_cvt_pk_bf16_f32 v11, v14, v15
	global_store_dwordx4 v[34:35], v[8:11], off offset:2064
	s_cbranch_scc1 .LBB0_1640
